# attn diffloop: hoist X2 LDS reads + trips1-3 X2 fast-path exps into PV MFMA gaps
# baseline (speedup 1.0000x reference)
.LBB0_182:
	s_add_i32 s0, s97, 0xffffff40
	s_and_b32 s99, s0, 0xfc0
	s_mul_i32 s18, s99, 0x1200
	v_lshl_add_u64 v[114:115], v[160:161], 0, s[18:19]
	s_waitcnt vmcnt(4)
	s_barrier
	v_lshl_add_u64 v[116:117], v[114:115], 0, s[22:23]
	s_add_i32 m0, s85, 0xc000
	s_nop 0
	global_load_lds_dwordx4 v[116:117], off
	v_lshl_add_u64 v[116:117], v[114:115], 0, s[56:57]
	s_add_i32 m0, s85, 0xe000
	s_nop 0
	global_load_lds_dwordx4 v[116:117], off
	v_lshl_add_u64 v[116:117], v[114:115], 0, s[68:69]
	s_add_i32 m0, s85, 0x1c000
	v_lshl_add_u64 v[114:115], v[114:115], 0, s[46:47]
	global_load_lds_dwordx4 v[116:117], off
	s_add_i32 m0, s85, 0x1e000
	s_nop 0
	global_load_lds_dwordx4 v[114:115], off
	ds_read_b128 v[146:149], v169 offset:8192
	ds_read_b128 v[150:153], v170 offset:8192
	ds_read_b128 v[182:185], v171 offset:8192
	ds_read_b128 v[198:201], v172 offset:8192
	ds_read_b64_tr_b16 v[118:119], v173
	ds_read_b64_tr_b16 v[120:121], v174
	ds_read_b64_tr_b16 v[124:125], v174 offset:4096
	ds_read_b64_tr_b16 v[122:123], v173 offset:4096
	ds_read_b64_tr_b16 v[134:135], v175
	ds_read_b64_tr_b16 v[136:137], v176
	ds_read_b64_tr_b16 v[132:133], v176 offset:4096
	ds_read_b64_tr_b16 v[130:131], v175 offset:4096
	ds_read_b64_tr_b16 v[138:139], v177
	ds_read_b64_tr_b16 v[140:141], v178
	ds_read_b64_tr_b16 v[128:129], v178 offset:4096
	ds_read_b64_tr_b16 v[126:127], v177 offset:4096
	ds_read_b64_tr_b16 v[142:143], v179
	ds_read_b64_tr_b16 v[144:145], v180
	ds_read_b64_tr_b16 v[116:117], v180 offset:4096
	ds_read_b64_tr_b16 v[114:115], v179 offset:4096
	s_waitcnt lgkmcnt(0)
	v_mfma_f32_32x32x16_bf16 v[82:97], v[146:149], v[98:101], v[82:97]
	s_and_b64 vcc, exec, s[44:45]
	s_mov_b64 s[42:43], s[44:45]
	v_mfma_f32_32x32x16_bf16 v[82:97], v[150:153], v[102:105], v[82:97]
	v_mfma_f32_32x32x16_bf16 v[82:97], v[182:185], v[106:109], v[82:97]
	v_mfma_f32_32x32x16_bf16 v[82:97], v[198:201], v[110:113], v[82:97]
	s_cbranch_vccnz .LBB0_184
	v_exp_f32_e32 v185, v66
	v_exp_f32_e32 v198, v67
	v_exp_f32_e32 v199, v68
	v_exp_f32_e32 v200, v69
	v_add_f32_e32 v201, 0, v185
	v_exp_f32_e32 v202, v70
	v_add_f32_e32 v201, v198, v201
	v_exp_f32_e32 v203, v71
	v_add_f32_e32 v201, v199, v201
	v_exp_f32_e32 v204, v72
	v_add_f32_e32 v201, v200, v201
	v_exp_f32_e32 v205, v73
	v_exp_f32_e32 v150, v74
	v_exp_f32_e32 v151, v75
	v_add_f32_e32 v201, v202, v201
	v_add_f32_e32 v201, v203, v201
	v_exp_f32_e32 v152, v76
	v_add_f32_e32 v201, v204, v201
	v_exp_f32_e32 v153, v77
	v_add_f32_e32 v201, v205, v201
	v_exp_f32_e32 v164, v78
	v_cvt_pk_bf16_f32 v146, v150, v151
	v_add_f32_e32 v150, v150, v201
	v_exp_f32_e32 v182, v79
	v_add_f32_e32 v150, v151, v150
	v_exp_f32_e32 v183, v80
	v_add_f32_e32 v150, v152, v150
	v_exp_f32_e32 v184, v81
	v_add_f32_e32 v150, v153, v150
	v_add_f32_e32 v150, v164, v150
	v_add_f32_e32 v150, v182, v150
	v_add_f32_e32 v150, v183, v150
	v_cvt_pk_bf16_f32 v148, v164, v182
	v_add_f32_e32 v247, v184, v150
	v_cmp_nge_f32_e32 vcc, s12, v247
	s_cmp_lg_u64 vcc, 0
	v_cvt_pk_bf16_f32 v147, v152, v153
	v_cvt_pk_bf16_f32 v149, v183, v184
	v_cvt_pk_bf16_f32 v150, v185, v198
	v_cvt_pk_bf16_f32 v151, v199, v200
	v_cvt_pk_bf16_f32 v152, v202, v203
	v_cvt_pk_bf16_f32 v153, v204, v205
	s_cselect_b64 s[42:43], -1, 0
.LBB0_184:
	s_andn2_b64 vcc, exec, s[42:43]
	s_cbranch_vccnz .LBB0_186
	v_max_f32_e32 v146, v67, v67
	v_max_f32_e32 v147, v66, v66
	v_max_f32_e32 v146, v147, v146
	v_max3_f32 v146, v146, v68, v69
	v_max3_f32 v146, v146, v70, v71
	v_max3_f32 v146, v146, v72, v73
	v_max3_f32 v146, v146, v74, v75
	v_max3_f32 v146, v146, v76, v77
	v_max3_f32 v146, v146, v78, v79
	v_max3_f32 v146, v146, v80, v81
	ds_bpermute_b32 v147, v159, v146
	s_waitcnt lgkmcnt(0)
	v_max_f32_e32 v147, v147, v147
	v_max_f32_e32 v146, v146, v147
	v_max_f32_e32 v147, 0, v146
	v_cndmask_b32_e64 v146, v147, v146, s[44:45]
	v_sub_f32_e32 v66, v66, v146
	v_exp_f32_e32 v66, v66
	v_sub_f32_e32 v67, v67, v146
	v_exp_f32_e32 v67, v67
	v_sub_f32_e32 v68, v68, v146
	v_exp_f32_e32 v68, v68
	v_sub_f32_e32 v69, v69, v146
	v_exp_f32_e32 v69, v69
	v_sub_f32_e32 v70, v70, v146
	v_add_f32_e32 v147, 0, v66
	v_exp_f32_e32 v70, v70
	v_sub_f32_e32 v71, v71, v146
	v_add_f32_e32 v147, v67, v147
	v_exp_f32_e32 v71, v71
	v_sub_f32_e32 v72, v72, v146
	v_add_f32_e32 v147, v68, v147
	v_exp_f32_e32 v72, v72
	v_sub_f32_e32 v73, v73, v146
	v_add_f32_e32 v147, v69, v147
	v_exp_f32_e32 v73, v73
	v_cvt_pk_bf16_f32 v150, v66, v67
	v_sub_f32_e32 v66, v74, v146
	v_add_f32_e32 v147, v70, v147
	v_exp_f32_e32 v66, v66
	v_sub_f32_e32 v67, v75, v146
	v_add_f32_e32 v147, v71, v147
	v_cvt_pk_bf16_f32 v151, v68, v69
	v_exp_f32_e32 v67, v67
	v_sub_f32_e32 v68, v76, v146
	v_add_f32_e32 v147, v72, v147
	v_exp_f32_e32 v68, v68
	v_sub_f32_e32 v69, v77, v146
	v_add_f32_e32 v147, v73, v147
	v_cvt_pk_bf16_f32 v152, v70, v71
	v_exp_f32_e32 v69, v69
	v_sub_f32_e32 v71, v78, v146
	v_cvt_pk_bf16_f32 v153, v72, v73
	v_add_f32_e32 v70, v66, v147
	v_exp_f32_e32 v71, v71
	v_sub_f32_e32 v72, v79, v146
	v_add_f32_e32 v70, v67, v70
	v_exp_f32_e32 v72, v72
	v_sub_f32_e32 v73, v80, v146
	v_add_f32_e32 v70, v68, v70
	v_exp_f32_e32 v73, v73
	v_sub_f32_e32 v74, v81, v146
	v_exp_f32_e64 v164, -v146
	v_add_f32_e32 v70, v69, v70
	v_exp_f32_e32 v74, v74
	v_add_f32_e32 v70, v71, v70
	v_add_f32_e32 v70, v72, v70
	v_add_f32_e32 v70, v73, v70
	v_add_f32_e32 v0, v0, v146
	v_pk_mul_f32 v[64:65], v[64:65], v[164:165] op_sel_hi:[1,0]
	v_pk_mul_f32 v[62:63], v[62:63], v[164:165] op_sel_hi:[1,0]
	v_pk_mul_f32 v[60:61], v[60:61], v[164:165] op_sel_hi:[1,0]
	v_pk_mul_f32 v[58:59], v[58:59], v[164:165] op_sel_hi:[1,0]
	v_pk_mul_f32 v[56:57], v[56:57], v[164:165] op_sel_hi:[1,0]
	v_pk_mul_f32 v[54:55], v[54:55], v[164:165] op_sel_hi:[1,0]
	v_pk_mul_f32 v[52:53], v[52:53], v[164:165] op_sel_hi:[1,0]
	v_pk_mul_f32 v[50:51], v[50:51], v[164:165] op_sel_hi:[1,0]
	v_pk_mul_f32 v[48:49], v[48:49], v[164:165] op_sel_hi:[1,0]
	v_pk_mul_f32 v[46:47], v[46:47], v[164:165] op_sel_hi:[1,0]
	v_pk_mul_f32 v[44:45], v[44:45], v[164:165] op_sel_hi:[1,0]
	v_pk_mul_f32 v[42:43], v[42:43], v[164:165] op_sel_hi:[1,0]
	v_pk_mul_f32 v[40:41], v[40:41], v[164:165] op_sel_hi:[1,0]
	v_pk_mul_f32 v[38:39], v[38:39], v[164:165] op_sel_hi:[1,0]
	v_pk_mul_f32 v[36:37], v[36:37], v[164:165] op_sel_hi:[1,0]
	v_pk_mul_f32 v[34:35], v[34:35], v[164:165] op_sel_hi:[1,0]
	v_pk_mul_f32 v[32:33], v[32:33], v[164:165] op_sel_hi:[1,0]
	v_pk_mul_f32 v[30:31], v[30:31], v[164:165] op_sel_hi:[1,0]
	v_pk_mul_f32 v[28:29], v[28:29], v[164:165] op_sel_hi:[1,0]
	v_pk_mul_f32 v[26:27], v[26:27], v[164:165] op_sel_hi:[1,0]
	v_pk_mul_f32 v[24:25], v[24:25], v[164:165] op_sel_hi:[1,0]
	v_pk_mul_f32 v[22:23], v[22:23], v[164:165] op_sel_hi:[1,0]
	v_pk_mul_f32 v[20:21], v[20:21], v[164:165] op_sel_hi:[1,0]
	v_pk_mul_f32 v[18:19], v[18:19], v[164:165] op_sel_hi:[1,0]
	v_pk_mul_f32 v[16:17], v[16:17], v[164:165] op_sel_hi:[1,0]
	v_pk_mul_f32 v[14:15], v[14:15], v[164:165] op_sel_hi:[1,0]
	v_pk_mul_f32 v[12:13], v[12:13], v[164:165] op_sel_hi:[1,0]
	v_pk_mul_f32 v[10:11], v[10:11], v[164:165] op_sel_hi:[1,0]
	v_pk_mul_f32 v[8:9], v[8:9], v[164:165] op_sel_hi:[1,0]
	v_pk_mul_f32 v[6:7], v[6:7], v[164:165] op_sel_hi:[1,0]
	v_pk_mul_f32 v[4:5], v[4:5], v[164:165] op_sel_hi:[1,0]
	v_pk_mul_f32 v[2:3], v[2:3], v[164:165] op_sel_hi:[1,0]
	v_sub_f32_e32 v97, v97, v146
	v_sub_f32_e32 v96, v96, v146
	v_sub_f32_e32 v95, v95, v146
	v_sub_f32_e32 v94, v94, v146
	v_sub_f32_e32 v93, v93, v146
	v_sub_f32_e32 v92, v92, v146
	v_sub_f32_e32 v91, v91, v146
	v_sub_f32_e32 v90, v90, v146
	v_sub_f32_e32 v89, v89, v146
	v_sub_f32_e32 v88, v88, v146
	v_sub_f32_e32 v87, v87, v146
	v_sub_f32_e32 v86, v86, v146
	v_sub_f32_e32 v85, v85, v146
	v_sub_f32_e32 v84, v84, v146
	v_sub_f32_e32 v83, v83, v146
	v_sub_f32_e32 v82, v82, v146
	v_add_f32_e32 v247, v74, v70
	v_cvt_pk_bf16_f32 v146, v66, v67
	v_cvt_pk_bf16_f32 v147, v68, v69
	v_cvt_pk_bf16_f32 v148, v71, v72
	v_cvt_pk_bf16_f32 v149, v73, v74
	v_mul_f32_e32 v181, v181, v164
.LBB0_186:
	v_mfma_f32_32x32x16_bf16 v[50:65], v[118:121], v[150:153], v[50:65]
	ds_read_b128 v[182:185], v169 offset:16384
	ds_read_b128 v[198:201], v170 offset:16384
	ds_read_b128 v[202:205], v171 offset:16384
	s_add_i32 s0, s97, 0xfffffec0
	s_and_b32 s0, s0, 0xfc0
	v_or_b32_e32 v66, s0, v166
	v_sub_u32_e32 v66, v167, v66
	v_cvt_f32_i32_e32 v67, v66
	s_cmp_lt_u32 s0, s84
	s_cselect_b64 s[42:43], -1, 0
	v_mfma_f32_32x32x16_bf16 v[34:49], v[134:137], v[150:153], v[34:49]
	ds_read_b128 v[206:209], v172 offset:16384
	ds_read_b64_tr_b16 v[118:119], v179 offset:8192
	ds_read_b64_tr_b16 v[120:121], v180 offset:8192
	v_fma_f32 v80, -v158, |v67|, -v0
	s_cmp_lg_u32 s0, s84
	v_mfma_f32_32x32x16_bf16 v[18:33], v[138:141], v[150:153], v[18:33]
	ds_read_b64_tr_b16 v[134:135], v175 offset:12288
	ds_read_b64_tr_b16 v[136:137], v176 offset:12288
	ds_read_b64_tr_b16 v[138:139], v177 offset:12288
	v_mfma_f32_32x32x16_bf16 v[2:17], v[142:145], v[150:153], v[2:17]
	ds_read_b64_tr_b16 v[140:141], v178 offset:12288
	ds_read_b64_tr_b16 v[142:143], v179 offset:12288
	ds_read_b64_tr_b16 v[144:145], v180 offset:12288
	v_mfma_f32_32x32x16_bf16 v[50:65], v[122:125], v[146:149], v[50:65]
	ds_read_b64_tr_b16 v[122:123], v177 offset:8192
	ds_read_b64_tr_b16 v[124:125], v178 offset:8192
	v_mfma_f32_32x32x16_bf16 v[34:49], v[130:133], v[146:149], v[34:49]
	ds_read_b64_tr_b16 v[130:131], v173 offset:8192
	ds_read_b64_tr_b16 v[132:133], v174 offset:8192
	v_mfma_f32_32x32x16_bf16 v[18:33], v[126:129], v[146:149], v[18:33]
	ds_read_b64_tr_b16 v[126:127], v175 offset:8192
	ds_read_b64_tr_b16 v[128:129], v176 offset:8192
	v_mfma_f32_32x32x16_bf16 v[2:17], v[114:117], v[146:149], v[2:17]
	ds_read_b64_tr_b16 v[114:115], v173 offset:12288
	ds_read_b64_tr_b16 v[116:117], v174 offset:12288
	s_cbranch_scc1 .LBB0_188
	v_add_u32_e32 v67, -2, v66
	v_cvt_f32_i32_e32 v67, v67
	v_add_u32_e32 v68, -1, v66
	v_cvt_f32_i32_e32 v68, v68
	v_add_u32_e32 v70, -8, v66
	v_and_b32_e32 v69, 0x7fffffff, v67
	v_add_u32_e32 v67, -3, v66
	v_cvt_f32_i32_e32 v67, v67
	v_cvt_f32_i32_e32 v70, v70
	v_and_b32_e32 v68, 0x7fffffff, v68
	v_pk_fma_f32 v[210:211], v[162:163], v[68:69], v[0:1] op_sel_hi:[1,1,0] neg_lo:[0,0,1] neg_hi:[0,0,1]
	v_and_b32_e32 v68, 0x7fffffff, v67
	v_add_u32_e32 v67, -10, v66
	v_cvt_f32_i32_e32 v67, v67
	v_and_b32_e32 v69, 0x7fffffff, v70
	v_pk_fma_f32 v[212:213], v[162:163], v[68:69], v[0:1] op_sel_hi:[1,1,0] neg_lo:[0,0,1] neg_hi:[0,0,1]
	v_add_u32_e32 v68, -9, v66
	v_cvt_f32_i32_e32 v68, v68
	v_and_b32_e32 v69, 0x7fffffff, v67
	v_add_u32_e32 v67, -16, v66
	v_cvt_f32_i32_e32 v67, v67
	v_add_u32_e32 v70, -11, v66
	v_cvt_f32_i32_e32 v70, v70
	v_and_b32_e32 v68, 0x7fffffff, v68
	v_pk_fma_f32 v[214:215], v[162:163], v[68:69], v[0:1] op_sel_hi:[1,1,0] neg_lo:[0,0,1] neg_hi:[0,0,1]
	v_and_b32_e32 v69, 0x7fffffff, v67
	v_subrev_u32_e32 v67, 18, v66
	v_cvt_f32_i32_e32 v67, v67
	v_and_b32_e32 v68, 0x7fffffff, v70
	v_pk_fma_f32 v[216:217], v[162:163], v[68:69], v[0:1] op_sel_hi:[1,1,0] neg_lo:[0,0,1] neg_hi:[0,0,1]
	v_subrev_u32_e32 v68, 17, v66
	v_cvt_f32_i32_e32 v68, v68
	v_and_b32_e32 v69, 0x7fffffff, v67
	v_subrev_u32_e32 v67, 24, v66
	v_subrev_u32_e32 v70, 19, v66
	v_cvt_f32_i32_e32 v67, v67
	v_cvt_f32_i32_e32 v70, v70
	v_and_b32_e32 v68, 0x7fffffff, v68
	v_pk_fma_f32 v[218:219], v[162:163], v[68:69], v[0:1] op_sel_hi:[1,1,0] neg_lo:[0,0,1] neg_hi:[0,0,1]
	v_and_b32_e32 v69, 0x7fffffff, v67
	v_and_b32_e32 v68, 0x7fffffff, v70
	v_pk_fma_f32 v[220:221], v[162:163], v[68:69], v[0:1] op_sel_hi:[1,1,0] neg_lo:[0,0,1] neg_hi:[0,0,1]
	v_subrev_u32_e32 v67, 26, v66
	v_subrev_u32_e32 v68, 25, v66
	v_cvt_f32_i32_e32 v67, v67
	v_cvt_f32_i32_e32 v68, v68
	v_subrev_u32_e32 v66, 27, v66
	v_cvt_f32_i32_e32 v69, v66
	v_and_b32_e32 v67, 0x7fffffff, v67
	v_and_b32_e32 v66, 0x7fffffff, v68
	v_mov_b32_e32 v81, v210
	v_pk_fma_f32 v[222:223], v[162:163], v[66:67], v[0:1] op_sel_hi:[1,1,0] neg_lo:[0,0,1] neg_hi:[0,0,1]
	v_fma_f32 v224, -v158, |v69|, -v0
	v_mov_b64_e32 v[66:67], v[80:81]
	v_mov_b64_e32 v[68:69], v[82:83]
	v_mov_b64_e32 v[70:71], v[84:85]
	v_mov_b64_e32 v[72:73], v[86:87]
	v_mov_b64_e32 v[74:75], v[88:89]
	v_mov_b64_e32 v[76:77], v[90:91]
	v_mov_b64_e32 v[78:79], v[92:93]
	v_mov_b64_e32 v[80:81], v[94:95]
	v_mov_b32_e32 v68, v211
	v_mov_b32_e32 v69, v212
	v_mov_b32_e32 v70, v213
	v_mov_b32_e32 v71, v214
	v_mov_b32_e32 v72, v215
	v_mov_b32_e32 v73, v216
	v_mov_b32_e32 v74, v217
	v_mov_b32_e32 v75, v218
	v_mov_b32_e32 v76, v219
	v_mov_b32_e32 v77, v220
	v_mov_b32_e32 v78, v221
	v_mov_b32_e32 v79, v222
	v_mov_b32_e32 v80, v223
	v_mov_b32_e32 v81, v224
	s_branch .LBB0_189
.LBB0_188:
	v_cndmask_b32_e64 v244, -v158, v158, s[42:43]
	v_fma_f32 v66, 0, v244, v80
	v_add_f32_e32 v67, v244, v80
	v_pk_fma_f32 v[68:69], v[244:245], s[26:27], v[80:81] op_sel_hi:[0,1,0]
	v_pk_fma_f32 v[70:71], v[244:245], s[28:29], v[80:81] op_sel_hi:[0,1,0]
	v_pk_fma_f32 v[72:73], v[244:245], s[30:31], v[80:81] op_sel_hi:[0,1,0]
	v_pk_fma_f32 v[74:75], v[244:245], s[34:35], v[80:81] op_sel_hi:[0,1,0]
	v_pk_fma_f32 v[76:77], v[244:245], s[36:37], v[80:81] op_sel_hi:[0,1,0]
	v_pk_fma_f32 v[78:79], v[244:245], s[14:15], v[80:81] op_sel_hi:[0,1,0]
	v_pk_fma_f32 v[80:81], v[244:245], s[10:11], v[80:81] op_sel_hi:[0,1,0]
.LBB0_189:
	v_add_f32_e32 v147, v247, v181
	s_waitcnt lgkmcnt(0)
	v_mfma_f32_32x32x16_bf16 v[66:81], v[182:185], v[98:101], v[66:81]
	v_exp_f32_e32 v149, v82
	v_exp_f32_e32 v150, v83
	v_exp_f32_e32 v151, v84
	v_exp_f32_e32 v152, v85
	v_add_f32_e32 v146, 0, v149
	v_exp_f32_e32 v153, v86
	v_add_f32_e32 v146, v150, v146
	v_mfma_f32_32x32x16_bf16 v[66:81], v[198:201], v[102:105], v[66:81]
	v_exp_f32_e32 v164, v87
	v_add_f32_e32 v146, v151, v146
	v_exp_f32_e32 v181, v88
	v_add_f32_e32 v146, v152, v146
	v_exp_f32_e32 v182, v89
	v_add_f32_e32 v146, v153, v146
	v_exp_f32_e32 v183, v90
	v_mfma_f32_32x32x16_bf16 v[66:81], v[202:205], v[106:109], v[66:81]
	v_add_f32_e32 v146, v164, v146
	v_exp_f32_e32 v184, v91
	v_add_f32_e32 v146, v181, v146
	v_exp_f32_e32 v185, v92
	v_add_f32_e32 v146, v182, v146
	v_exp_f32_e32 v198, v93
	v_add_f32_e32 v146, v183, v146
	v_exp_f32_e32 v199, v94
	v_add_f32_e32 v146, v184, v146
	v_exp_f32_e32 v200, v95
	v_mfma_f32_32x32x16_bf16 v[66:81], v[206:209], v[110:113], v[66:81]
	v_add_f32_e32 v146, v185, v146
	v_exp_f32_e32 v201, v96
	v_add_f32_e32 v146, v198, v146
	v_exp_f32_e32 v202, v97
	v_add_f32_e32 v146, v199, v146
	v_add_f32_e32 v146, v200, v146
	v_add_f32_e32 v146, v201, v146
	v_add_f32_e32 v148, v202, v146
	v_cmp_nge_f32_e32 vcc, s12, v148
	s_cbranch_vccz .LBB0_191
	v_max_f32_e32 v146, v83, v83
	v_max_f32_e32 v148, v82, v82
	v_max_f32_e32 v146, v148, v146
	v_max3_f32 v146, v146, v84, v85
	v_max3_f32 v146, v146, v86, v87
	v_max3_f32 v146, v146, v88, v89
	v_max3_f32 v146, v146, v90, v91
	v_max3_f32 v146, v146, v92, v93
	v_max3_f32 v146, v146, v94, v95
	v_max3_f32 v146, v146, v96, v97
	ds_bpermute_b32 v148, v159, v146
	s_waitcnt lgkmcnt(0)
	v_max3_f32 v148, v146, v148, 0
	v_sub_f32_e32 v82, v82, v148
	v_exp_f32_e32 v82, v82
	v_sub_f32_e32 v83, v83, v148
	v_exp_f32_e32 v83, v83
	v_sub_f32_e32 v84, v84, v148
	v_exp_f32_e32 v84, v84
	v_sub_f32_e32 v85, v85, v148
	v_exp_f32_e32 v85, v85
	v_sub_f32_e32 v86, v86, v148
	v_sub_f32_e32 v87, v87, v148
	v_add_f32_e32 v149, 0, v82
	v_exp_f32_e32 v86, v86
	v_exp_f32_e32 v87, v87
	v_add_f32_e32 v149, v83, v149
	v_sub_f32_e32 v88, v88, v148
	v_sub_f32_e32 v89, v89, v148
	v_add_f32_e32 v149, v84, v149
	v_exp_f32_e32 v88, v88
	v_exp_f32_e32 v89, v89
	v_add_f32_e32 v149, v85, v149
	v_add_f32_e32 v149, v86, v149
	v_cvt_pk_bf16_f32 v82, v82, v83
	v_cvt_pk_bf16_f32 v83, v84, v85
	v_cvt_pk_bf16_f32 v84, v86, v87
	v_sub_f32_e32 v86, v90, v148
	v_add_f32_e32 v149, v87, v149
	v_exp_f32_e32 v86, v86
	v_sub_f32_e32 v87, v91, v148
	v_add_f32_e32 v149, v88, v149
	v_cvt_pk_bf16_f32 v85, v88, v89
	v_exp_f32_e32 v87, v87
	v_sub_f32_e32 v88, v92, v148
	v_add_f32_e32 v149, v89, v149
	v_exp_f32_e32 v88, v88
	v_sub_f32_e32 v89, v93, v148
	v_exp_f32_e32 v89, v89
	v_sub_f32_e32 v91, v94, v148
	v_add_f32_e32 v90, v86, v149
	v_exp_f32_e32 v91, v91
	v_sub_f32_e32 v92, v95, v148
	v_add_f32_e32 v90, v87, v90
	v_exp_f32_e32 v92, v92
	v_sub_f32_e32 v93, v96, v148
	v_add_f32_e32 v90, v88, v90
	v_exp_f32_e32 v93, v93
	v_sub_f32_e32 v94, v97, v148
	v_exp_f32_e64 v146, -v148
	v_add_f32_e32 v90, v89, v90
	v_exp_f32_e32 v94, v94
	v_add_f32_e32 v90, v91, v90
	v_add_f32_e32 v90, v92, v90
	v_add_f32_e32 v0, v0, v148
	v_add_f32_e32 v90, v93, v90
	v_pk_mul_f32 v[64:65], v[64:65], v[146:147] op_sel_hi:[1,0]
	v_pk_mul_f32 v[62:63], v[62:63], v[146:147] op_sel_hi:[1,0]
	v_pk_mul_f32 v[60:61], v[60:61], v[146:147] op_sel_hi:[1,0]
	v_pk_mul_f32 v[58:59], v[58:59], v[146:147] op_sel_hi:[1,0]
	v_pk_mul_f32 v[56:57], v[56:57], v[146:147] op_sel_hi:[1,0]
	v_pk_mul_f32 v[54:55], v[54:55], v[146:147] op_sel_hi:[1,0]
	v_pk_mul_f32 v[52:53], v[52:53], v[146:147] op_sel_hi:[1,0]
	v_pk_mul_f32 v[50:51], v[50:51], v[146:147] op_sel_hi:[1,0]
	v_pk_mul_f32 v[48:49], v[48:49], v[146:147] op_sel_hi:[1,0]
	v_pk_mul_f32 v[46:47], v[46:47], v[146:147] op_sel_hi:[1,0]
	v_pk_mul_f32 v[44:45], v[44:45], v[146:147] op_sel_hi:[1,0]
	v_pk_mul_f32 v[42:43], v[42:43], v[146:147] op_sel_hi:[1,0]
	v_pk_mul_f32 v[40:41], v[40:41], v[146:147] op_sel_hi:[1,0]
	v_pk_mul_f32 v[38:39], v[38:39], v[146:147] op_sel_hi:[1,0]
	v_pk_mul_f32 v[36:37], v[36:37], v[146:147] op_sel_hi:[1,0]
	v_pk_mul_f32 v[34:35], v[34:35], v[146:147] op_sel_hi:[1,0]
	v_pk_mul_f32 v[32:33], v[32:33], v[146:147] op_sel_hi:[1,0]
	v_pk_mul_f32 v[30:31], v[30:31], v[146:147] op_sel_hi:[1,0]
	v_pk_mul_f32 v[28:29], v[28:29], v[146:147] op_sel_hi:[1,0]
	v_pk_mul_f32 v[26:27], v[26:27], v[146:147] op_sel_hi:[1,0]
	v_pk_mul_f32 v[24:25], v[24:25], v[146:147] op_sel_hi:[1,0]
	v_pk_mul_f32 v[22:23], v[22:23], v[146:147] op_sel_hi:[1,0]
	v_pk_mul_f32 v[20:21], v[20:21], v[146:147] op_sel_hi:[1,0]
	v_pk_mul_f32 v[18:19], v[18:19], v[146:147] op_sel_hi:[1,0]
	v_pk_mul_f32 v[16:17], v[16:17], v[146:147] op_sel_hi:[1,0]
	v_pk_mul_f32 v[14:15], v[14:15], v[146:147] op_sel_hi:[1,0]
	v_pk_mul_f32 v[12:13], v[12:13], v[146:147] op_sel_hi:[1,0]
	v_pk_mul_f32 v[10:11], v[10:11], v[146:147] op_sel_hi:[1,0]
	v_pk_mul_f32 v[8:9], v[8:9], v[146:147] op_sel_hi:[1,0]
	v_pk_mul_f32 v[6:7], v[6:7], v[146:147] op_sel_hi:[1,0]
	v_pk_mul_f32 v[4:5], v[4:5], v[146:147] op_sel_hi:[1,0]
	v_pk_mul_f32 v[2:3], v[2:3], v[146:147] op_sel_hi:[1,0]
	v_sub_f32_e32 v81, v81, v148
	v_sub_f32_e32 v80, v80, v148
	v_sub_f32_e32 v79, v79, v148
	v_sub_f32_e32 v78, v78, v148
	v_sub_f32_e32 v77, v77, v148
	v_sub_f32_e32 v76, v76, v148
	v_sub_f32_e32 v75, v75, v148
	v_sub_f32_e32 v74, v74, v148
	v_sub_f32_e32 v73, v73, v148
	v_sub_f32_e32 v72, v72, v148
	v_sub_f32_e32 v71, v71, v148
	v_sub_f32_e32 v70, v70, v148
	v_sub_f32_e32 v69, v69, v148
	v_sub_f32_e32 v68, v68, v148
	v_sub_f32_e32 v67, v67, v148
	v_sub_f32_e32 v66, v66, v148
	v_add_f32_e32 v148, v94, v90
	v_cvt_pk_bf16_f32 v86, v86, v87
	v_cvt_pk_bf16_f32 v87, v88, v89
	v_cvt_pk_bf16_f32 v88, v91, v92
	v_cvt_pk_bf16_f32 v89, v93, v94
	v_mul_f32_e32 v147, v147, v146
	v_xor_b32_e32 v146, 0x80000000, v0
	s_branch .LBB0_192

.LBB0_200:
	v_mfma_f32_32x32x16_bf16 v[50:65], v[130:133], v[66:69], v[50:65]
	ds_read_b128 v[182:185], v169 offset:32768
	ds_read_b128 v[198:201], v170 offset:32768
	ds_read_b128 v[202:205], v171 offset:32768
	v_exp_f32_e32 v149, v82
	v_exp_f32_e32 v150, v83
	s_add_i32 s0, s97, 0xffffff00
	s_and_b32 s0, s0, 0xf80
	s_cmp_lt_u32 s0, s84
	s_cselect_b64 s[44:45], -1, 0
	s_cmp_lg_u32 s0, s84
	v_mfma_f32_32x32x16_bf16 v[34:49], v[126:129], v[66:69], v[34:49]
	ds_read_b128 v[206:209], v172 offset:32768
	ds_read_b64_tr_b16 v[130:131], v173 offset:24576
	ds_read_b64_tr_b16 v[132:133], v174 offset:24576
	v_exp_f32_e32 v151, v84
	v_exp_f32_e32 v152, v85
	v_mfma_f32_32x32x16_bf16 v[18:33], v[122:125], v[66:69], v[18:33]
	ds_read_b64_tr_b16 v[126:127], v175 offset:24576
	ds_read_b64_tr_b16 v[128:129], v176 offset:24576
	ds_read_b64_tr_b16 v[122:123], v177 offset:24576
	v_exp_f32_e32 v153, v86
	v_exp_f32_e32 v164, v87
	v_mfma_f32_32x32x16_bf16 v[2:17], v[118:121], v[66:69], v[2:17]
	ds_read_b64_tr_b16 v[124:125], v178 offset:24576
	ds_read_b64_tr_b16 v[118:119], v179 offset:24576
	ds_read_b64_tr_b16 v[120:121], v180 offset:24576
	v_exp_f32_e32 v181, v88
	v_exp_f32_e32 v225, v89
	v_or_b32_e32 v66, s0, v166
	v_sub_u32_e32 v66, v167, v66
	v_cvt_f32_i32_e32 v67, v66
	v_fma_f32 v80, -v158, |v67|, v146
	v_mfma_f32_32x32x16_bf16 v[50:65], v[114:117], v[70:73], v[50:65]
	ds_read_b64_tr_b16 v[114:115], v173 offset:28672
	ds_read_b64_tr_b16 v[116:117], v174 offset:28672
	v_exp_f32_e32 v226, v90
	v_exp_f32_e32 v227, v91
	v_mfma_f32_32x32x16_bf16 v[34:49], v[134:137], v[70:73], v[34:49]
	ds_read_b64_tr_b16 v[134:135], v175 offset:28672
	ds_read_b64_tr_b16 v[136:137], v176 offset:28672
	v_exp_f32_e32 v239, v92
	v_exp_f32_e32 v240, v93
	v_mfma_f32_32x32x16_bf16 v[18:33], v[138:141], v[70:73], v[18:33]
	ds_read_b64_tr_b16 v[138:139], v177 offset:28672
	ds_read_b64_tr_b16 v[140:141], v178 offset:28672
	v_exp_f32_e32 v241, v94
	v_exp_f32_e32 v242, v95
	v_mfma_f32_32x32x16_bf16 v[2:17], v[142:145], v[70:73], v[2:17]
	ds_read_b64_tr_b16 v[142:143], v179 offset:28672
	ds_read_b64_tr_b16 v[144:145], v180 offset:28672
	v_exp_f32_e32 v243, v96
	v_exp_f32_e32 v246, v97
	s_cbranch_scc1 .LBB0_202
	v_add_u32_e32 v67, -2, v66
	v_cvt_f32_i32_e32 v67, v67
	v_add_u32_e32 v68, -1, v66
	v_cvt_f32_i32_e32 v68, v68
	v_add_u32_e32 v70, -8, v66
	v_and_b32_e32 v69, 0x7fffffff, v67
	v_add_u32_e32 v67, -3, v66
	v_cvt_f32_i32_e32 v67, v67
	v_cvt_f32_i32_e32 v70, v70
	v_and_b32_e32 v68, 0x7fffffff, v68
	v_pk_fma_f32 v[210:211], v[162:163], v[68:69], v[146:147] op_sel_hi:[1,1,0]
	v_and_b32_e32 v68, 0x7fffffff, v67
	v_add_u32_e32 v67, -10, v66
	v_cvt_f32_i32_e32 v67, v67
	v_and_b32_e32 v69, 0x7fffffff, v70
	v_pk_fma_f32 v[212:213], v[162:163], v[68:69], v[146:147] op_sel_hi:[1,1,0]
	v_add_u32_e32 v68, -9, v66
	v_cvt_f32_i32_e32 v68, v68
	v_and_b32_e32 v69, 0x7fffffff, v67
	v_add_u32_e32 v67, -16, v66
	v_cvt_f32_i32_e32 v67, v67
	v_add_u32_e32 v70, -11, v66
	v_cvt_f32_i32_e32 v70, v70
	v_and_b32_e32 v68, 0x7fffffff, v68
	v_pk_fma_f32 v[214:215], v[162:163], v[68:69], v[146:147] op_sel_hi:[1,1,0]
	v_and_b32_e32 v69, 0x7fffffff, v67
	v_subrev_u32_e32 v67, 18, v66
	v_cvt_f32_i32_e32 v67, v67
	v_and_b32_e32 v68, 0x7fffffff, v70
	v_pk_fma_f32 v[216:217], v[162:163], v[68:69], v[146:147] op_sel_hi:[1,1,0]
	v_subrev_u32_e32 v68, 17, v66
	v_cvt_f32_i32_e32 v68, v68
	v_and_b32_e32 v69, 0x7fffffff, v67
	v_subrev_u32_e32 v67, 24, v66
	v_subrev_u32_e32 v70, 19, v66
	v_cvt_f32_i32_e32 v67, v67
	v_cvt_f32_i32_e32 v70, v70
	v_and_b32_e32 v68, 0x7fffffff, v68
	v_pk_fma_f32 v[218:219], v[162:163], v[68:69], v[146:147] op_sel_hi:[1,1,0]
	v_and_b32_e32 v69, 0x7fffffff, v67
	v_and_b32_e32 v68, 0x7fffffff, v70
	v_pk_fma_f32 v[220:221], v[162:163], v[68:69], v[146:147] op_sel_hi:[1,1,0]
	v_subrev_u32_e32 v67, 26, v66
	v_subrev_u32_e32 v68, 25, v66
	v_cvt_f32_i32_e32 v67, v67
	v_cvt_f32_i32_e32 v68, v68
	v_subrev_u32_e32 v66, 27, v66
	v_cvt_f32_i32_e32 v69, v66
	v_and_b32_e32 v67, 0x7fffffff, v67
	v_and_b32_e32 v66, 0x7fffffff, v68
	v_mov_b32_e32 v81, v210
	v_pk_fma_f32 v[222:223], v[162:163], v[66:67], v[146:147] op_sel_hi:[1,1,0]
	v_fma_f32 v224, -v158, |v69|, v146
	v_mov_b64_e32 v[66:67], v[80:81]
	v_mov_b64_e32 v[68:69], v[82:83]
	v_mov_b64_e32 v[70:71], v[84:85]
	v_mov_b64_e32 v[72:73], v[86:87]
	v_mov_b64_e32 v[74:75], v[88:89]
	v_mov_b64_e32 v[76:77], v[90:91]
	v_mov_b64_e32 v[78:79], v[92:93]
	v_mov_b64_e32 v[80:81], v[94:95]
	v_mov_b32_e32 v68, v211
	v_mov_b32_e32 v69, v212
	v_mov_b32_e32 v70, v213
	v_mov_b32_e32 v71, v214
	v_mov_b32_e32 v72, v215
	v_mov_b32_e32 v73, v216
	v_mov_b32_e32 v74, v217
	v_mov_b32_e32 v75, v218
	v_mov_b32_e32 v76, v219
	v_mov_b32_e32 v77, v220
	v_mov_b32_e32 v78, v221
	v_mov_b32_e32 v79, v222
	v_mov_b32_e32 v80, v223
	v_mov_b32_e32 v81, v224
	s_branch .LBB0_203
.LBB0_202:
	v_cndmask_b32_e64 v244, -v158, v158, s[44:45]
	v_fma_f32 v66, 0, v244, v80
	v_add_f32_e32 v67, v244, v80
	v_pk_fma_f32 v[68:69], v[244:245], s[26:27], v[80:81] op_sel_hi:[0,1,0]
	v_pk_fma_f32 v[70:71], v[244:245], s[28:29], v[80:81] op_sel_hi:[0,1,0]
	v_pk_fma_f32 v[72:73], v[244:245], s[30:31], v[80:81] op_sel_hi:[0,1,0]
	v_pk_fma_f32 v[74:75], v[244:245], s[34:35], v[80:81] op_sel_hi:[0,1,0]
	v_pk_fma_f32 v[76:77], v[244:245], s[36:37], v[80:81] op_sel_hi:[0,1,0]
	v_pk_fma_f32 v[78:79], v[244:245], s[14:15], v[80:81] op_sel_hi:[0,1,0]
	v_pk_fma_f32 v[80:81], v[244:245], s[10:11], v[80:81] op_sel_hi:[0,1,0]
.LBB0_203:
	v_add_f32_e32 v147, v148, v147
	s_waitcnt lgkmcnt(0)
	v_mfma_f32_32x32x16_bf16 v[66:81], v[182:185], v[98:101], v[66:81]
	v_add_f32_e32 v148, 0, v149
	v_add_f32_e32 v148, v150, v148
	v_mfma_f32_32x32x16_bf16 v[66:81], v[198:201], v[102:105], v[66:81]
	v_add_f32_e32 v148, v151, v148
	v_add_f32_e32 v148, v152, v148
	v_add_f32_e32 v148, v153, v148
	v_mfma_f32_32x32x16_bf16 v[66:81], v[202:205], v[106:109], v[66:81]
	v_add_f32_e32 v148, v164, v148
	v_add_f32_e32 v148, v181, v148
	v_add_f32_e32 v148, v225, v148
	v_add_f32_e32 v148, v226, v148
	v_add_f32_e32 v148, v227, v148
	v_mfma_f32_32x32x16_bf16 v[66:81], v[206:209], v[110:113], v[66:81]
	v_add_f32_e32 v148, v239, v148
	v_add_f32_e32 v148, v240, v148
	v_add_f32_e32 v148, v241, v148
	v_add_f32_e32 v148, v242, v148
	v_add_f32_e32 v148, v243, v148
	v_add_f32_e32 v148, v246, v148
	v_cmp_nge_f32_e32 vcc, s12, v148
	s_cbranch_vccz .LBB0_205
	v_max_f32_e32 v146, v83, v83
	v_max_f32_e32 v148, v82, v82
	v_max_f32_e32 v146, v148, v146
	v_max3_f32 v146, v146, v84, v85
	v_max3_f32 v146, v146, v86, v87
	v_max3_f32 v146, v146, v88, v89
	v_max3_f32 v146, v146, v90, v91
	v_max3_f32 v146, v146, v92, v93
	v_max3_f32 v146, v146, v94, v95
	v_max3_f32 v146, v146, v96, v97
	ds_bpermute_b32 v148, v159, v146
	s_waitcnt lgkmcnt(0)
	v_max3_f32 v148, v146, v148, 0
	v_sub_f32_e32 v82, v82, v148
	v_exp_f32_e32 v82, v82
	v_sub_f32_e32 v83, v83, v148
	v_exp_f32_e32 v83, v83
	v_sub_f32_e32 v84, v84, v148
	v_exp_f32_e32 v84, v84
	v_sub_f32_e32 v85, v85, v148
	v_exp_f32_e32 v85, v85
	v_sub_f32_e32 v86, v86, v148
	v_sub_f32_e32 v87, v87, v148
	v_add_f32_e32 v149, 0, v82
	v_exp_f32_e32 v86, v86
	v_exp_f32_e32 v87, v87
	v_add_f32_e32 v149, v83, v149
	v_sub_f32_e32 v88, v88, v148
	v_sub_f32_e32 v89, v89, v148
	v_add_f32_e32 v149, v84, v149
	v_exp_f32_e32 v88, v88
	v_exp_f32_e32 v89, v89
	v_add_f32_e32 v149, v85, v149
	v_add_f32_e32 v149, v86, v149
	v_cvt_pk_bf16_f32 v82, v82, v83
	v_cvt_pk_bf16_f32 v83, v84, v85
	v_cvt_pk_bf16_f32 v84, v86, v87
	v_sub_f32_e32 v86, v90, v148
	v_add_f32_e32 v149, v87, v149
	v_exp_f32_e32 v86, v86
	v_sub_f32_e32 v87, v91, v148
	v_add_f32_e32 v149, v88, v149
	v_cvt_pk_bf16_f32 v85, v88, v89
	v_exp_f32_e32 v87, v87
	v_sub_f32_e32 v88, v92, v148
	v_add_f32_e32 v149, v89, v149
	v_exp_f32_e32 v88, v88
	v_sub_f32_e32 v89, v93, v148
	v_exp_f32_e32 v89, v89
	v_sub_f32_e32 v91, v94, v148
	v_add_f32_e32 v90, v86, v149
	v_exp_f32_e32 v91, v91
	v_sub_f32_e32 v92, v95, v148
	v_add_f32_e32 v90, v87, v90
	v_exp_f32_e32 v92, v92
	v_sub_f32_e32 v93, v96, v148
	v_add_f32_e32 v90, v88, v90
	v_exp_f32_e32 v93, v93
	v_sub_f32_e32 v94, v97, v148
	v_exp_f32_e64 v146, -v148
	v_add_f32_e32 v90, v89, v90
	v_exp_f32_e32 v94, v94
	v_add_f32_e32 v90, v91, v90
	v_add_f32_e32 v90, v92, v90
	v_add_f32_e32 v0, v0, v148
	v_add_f32_e32 v90, v93, v90
	v_pk_mul_f32 v[64:65], v[64:65], v[146:147] op_sel_hi:[1,0]
	v_pk_mul_f32 v[62:63], v[62:63], v[146:147] op_sel_hi:[1,0]
	v_pk_mul_f32 v[60:61], v[60:61], v[146:147] op_sel_hi:[1,0]
	v_pk_mul_f32 v[58:59], v[58:59], v[146:147] op_sel_hi:[1,0]
	v_pk_mul_f32 v[56:57], v[56:57], v[146:147] op_sel_hi:[1,0]
	v_pk_mul_f32 v[54:55], v[54:55], v[146:147] op_sel_hi:[1,0]
	v_pk_mul_f32 v[52:53], v[52:53], v[146:147] op_sel_hi:[1,0]
	v_pk_mul_f32 v[50:51], v[50:51], v[146:147] op_sel_hi:[1,0]
	v_pk_mul_f32 v[48:49], v[48:49], v[146:147] op_sel_hi:[1,0]
	v_pk_mul_f32 v[46:47], v[46:47], v[146:147] op_sel_hi:[1,0]
	v_pk_mul_f32 v[44:45], v[44:45], v[146:147] op_sel_hi:[1,0]
	v_pk_mul_f32 v[42:43], v[42:43], v[146:147] op_sel_hi:[1,0]
	v_pk_mul_f32 v[40:41], v[40:41], v[146:147] op_sel_hi:[1,0]
	v_pk_mul_f32 v[38:39], v[38:39], v[146:147] op_sel_hi:[1,0]
	v_pk_mul_f32 v[36:37], v[36:37], v[146:147] op_sel_hi:[1,0]
	v_pk_mul_f32 v[34:35], v[34:35], v[146:147] op_sel_hi:[1,0]
	v_pk_mul_f32 v[32:33], v[32:33], v[146:147] op_sel_hi:[1,0]
	v_pk_mul_f32 v[30:31], v[30:31], v[146:147] op_sel_hi:[1,0]
	v_pk_mul_f32 v[28:29], v[28:29], v[146:147] op_sel_hi:[1,0]
	v_pk_mul_f32 v[26:27], v[26:27], v[146:147] op_sel_hi:[1,0]
	v_pk_mul_f32 v[24:25], v[24:25], v[146:147] op_sel_hi:[1,0]
	v_pk_mul_f32 v[22:23], v[22:23], v[146:147] op_sel_hi:[1,0]
	v_pk_mul_f32 v[20:21], v[20:21], v[146:147] op_sel_hi:[1,0]
	v_pk_mul_f32 v[18:19], v[18:19], v[146:147] op_sel_hi:[1,0]
	v_pk_mul_f32 v[16:17], v[16:17], v[146:147] op_sel_hi:[1,0]
	v_pk_mul_f32 v[14:15], v[14:15], v[146:147] op_sel_hi:[1,0]
	v_pk_mul_f32 v[12:13], v[12:13], v[146:147] op_sel_hi:[1,0]
	v_pk_mul_f32 v[10:11], v[10:11], v[146:147] op_sel_hi:[1,0]
	v_pk_mul_f32 v[8:9], v[8:9], v[146:147] op_sel_hi:[1,0]
	v_pk_mul_f32 v[6:7], v[6:7], v[146:147] op_sel_hi:[1,0]
	v_pk_mul_f32 v[4:5], v[4:5], v[146:147] op_sel_hi:[1,0]
	v_pk_mul_f32 v[2:3], v[2:3], v[146:147] op_sel_hi:[1,0]
	v_sub_f32_e32 v81, v81, v148
	v_sub_f32_e32 v80, v80, v148
	v_sub_f32_e32 v79, v79, v148
	v_sub_f32_e32 v78, v78, v148
	v_sub_f32_e32 v77, v77, v148
	v_sub_f32_e32 v76, v76, v148
	v_sub_f32_e32 v75, v75, v148
	v_sub_f32_e32 v74, v74, v148
	v_sub_f32_e32 v73, v73, v148
	v_sub_f32_e32 v72, v72, v148
	v_sub_f32_e32 v71, v71, v148
	v_sub_f32_e32 v70, v70, v148
	v_sub_f32_e32 v69, v69, v148
	v_sub_f32_e32 v68, v68, v148
	v_sub_f32_e32 v67, v67, v148
	v_sub_f32_e32 v66, v66, v148
	v_add_f32_e32 v148, v94, v90
	v_cvt_pk_bf16_f32 v86, v86, v87
	v_cvt_pk_bf16_f32 v87, v88, v89
	v_cvt_pk_bf16_f32 v88, v91, v92
	v_cvt_pk_bf16_f32 v89, v93, v94
	v_mul_f32_e32 v147, v147, v146
	v_xor_b32_e32 v146, 0x80000000, v0
	s_branch .LBB0_206
.LBB0_205:
	v_cvt_pk_bf16_f32 v82, v149, v150
	v_cvt_pk_bf16_f32 v83, v151, v152
	v_cvt_pk_bf16_f32 v84, v153, v164
	v_cvt_pk_bf16_f32 v85, v181, v225
	v_cvt_pk_bf16_f32 v86, v226, v227
	v_cvt_pk_bf16_f32 v87, v239, v240
	v_cvt_pk_bf16_f32 v88, v241, v242
	v_cvt_pk_bf16_f32 v89, v243, v246

.LBB0_217:
	v_mfma_f32_32x32x16_bf16 v[50:65], v[130:133], v[66:69], v[50:65]
	ds_read_b128 v[182:185], v169 offset:49152
	ds_read_b128 v[198:201], v170 offset:49152
	ds_read_b128 v[202:205], v171 offset:49152
	v_exp_f32_e32 v149, v82
	v_exp_f32_e32 v150, v83
	s_cmp_lt_u32 s99, s84
	s_cselect_b64 s[48:49], -1, 0
	s_cmp_lg_u32 s99, s84
	v_mfma_f32_32x32x16_bf16 v[34:49], v[126:129], v[66:69], v[34:49]
	ds_read_b128 v[206:209], v172 offset:49152
	ds_read_b64_tr_b16 v[130:131], v173 offset:40960
	ds_read_b64_tr_b16 v[132:133], v174 offset:40960
	v_exp_f32_e32 v151, v84
	v_exp_f32_e32 v152, v85
	v_mfma_f32_32x32x16_bf16 v[18:33], v[122:125], v[66:69], v[18:33]
	ds_read_b64_tr_b16 v[126:127], v175 offset:40960
	ds_read_b64_tr_b16 v[128:129], v176 offset:40960
	ds_read_b64_tr_b16 v[122:123], v177 offset:40960
	v_exp_f32_e32 v153, v86
	v_exp_f32_e32 v164, v87
	v_mfma_f32_32x32x16_bf16 v[2:17], v[118:121], v[66:69], v[2:17]
	ds_read_b64_tr_b16 v[124:125], v178 offset:40960
	ds_read_b64_tr_b16 v[118:119], v179 offset:40960
	ds_read_b64_tr_b16 v[120:121], v180 offset:40960
	v_exp_f32_e32 v181, v88
	v_exp_f32_e32 v225, v89
	v_or_b32_e32 v66, s99, v166
	v_sub_u32_e32 v66, v167, v66
	v_cvt_f32_i32_e32 v67, v66
	v_fma_f32 v80, -v158, |v67|, v146
	v_mfma_f32_32x32x16_bf16 v[50:65], v[114:117], v[70:73], v[50:65]
	ds_read_b64_tr_b16 v[114:115], v173 offset:45056
	ds_read_b64_tr_b16 v[116:117], v174 offset:45056
	v_exp_f32_e32 v226, v90
	v_exp_f32_e32 v227, v91
	v_mfma_f32_32x32x16_bf16 v[34:49], v[134:137], v[70:73], v[34:49]
	ds_read_b64_tr_b16 v[134:135], v175 offset:45056
	ds_read_b64_tr_b16 v[136:137], v176 offset:45056
	v_exp_f32_e32 v239, v92
	v_exp_f32_e32 v240, v93
	v_mfma_f32_32x32x16_bf16 v[18:33], v[138:141], v[70:73], v[18:33]
	ds_read_b64_tr_b16 v[138:139], v177 offset:45056
	ds_read_b64_tr_b16 v[140:141], v178 offset:45056
	v_exp_f32_e32 v241, v94
	v_exp_f32_e32 v242, v95
	v_mfma_f32_32x32x16_bf16 v[2:17], v[142:145], v[70:73], v[2:17]
	ds_read_b64_tr_b16 v[142:143], v179 offset:45056
	ds_read_b64_tr_b16 v[144:145], v180 offset:45056
	v_exp_f32_e32 v243, v96
	v_exp_f32_e32 v246, v97
	s_cbranch_scc1 .LBB0_219
	v_add_u32_e32 v67, -2, v66
	v_cvt_f32_i32_e32 v67, v67
	v_add_u32_e32 v68, -1, v66
	v_cvt_f32_i32_e32 v68, v68
	v_add_u32_e32 v70, -8, v66
	v_and_b32_e32 v69, 0x7fffffff, v67
	v_add_u32_e32 v67, -3, v66
	v_cvt_f32_i32_e32 v67, v67
	v_cvt_f32_i32_e32 v70, v70
	v_and_b32_e32 v68, 0x7fffffff, v68
	v_pk_fma_f32 v[210:211], v[162:163], v[68:69], v[146:147] op_sel_hi:[1,1,0]
	v_and_b32_e32 v68, 0x7fffffff, v67
	v_add_u32_e32 v67, -10, v66
	v_cvt_f32_i32_e32 v67, v67
	v_and_b32_e32 v69, 0x7fffffff, v70
	v_pk_fma_f32 v[212:213], v[162:163], v[68:69], v[146:147] op_sel_hi:[1,1,0]
	v_add_u32_e32 v68, -9, v66
	v_cvt_f32_i32_e32 v68, v68
	v_and_b32_e32 v69, 0x7fffffff, v67
	v_add_u32_e32 v67, -16, v66
	v_cvt_f32_i32_e32 v67, v67
	v_add_u32_e32 v70, -11, v66
	v_cvt_f32_i32_e32 v70, v70
	v_and_b32_e32 v68, 0x7fffffff, v68
	v_pk_fma_f32 v[214:215], v[162:163], v[68:69], v[146:147] op_sel_hi:[1,1,0]
	v_and_b32_e32 v69, 0x7fffffff, v67
	v_subrev_u32_e32 v67, 18, v66
	v_cvt_f32_i32_e32 v67, v67
	v_and_b32_e32 v68, 0x7fffffff, v70
	v_pk_fma_f32 v[216:217], v[162:163], v[68:69], v[146:147] op_sel_hi:[1,1,0]
	v_subrev_u32_e32 v68, 17, v66
	v_cvt_f32_i32_e32 v68, v68
	v_and_b32_e32 v69, 0x7fffffff, v67
	v_subrev_u32_e32 v67, 24, v66
	v_subrev_u32_e32 v70, 19, v66
	v_cvt_f32_i32_e32 v67, v67
	v_cvt_f32_i32_e32 v70, v70
	v_and_b32_e32 v68, 0x7fffffff, v68
	v_pk_fma_f32 v[218:219], v[162:163], v[68:69], v[146:147] op_sel_hi:[1,1,0]
	v_and_b32_e32 v69, 0x7fffffff, v67
	v_and_b32_e32 v68, 0x7fffffff, v70
	v_pk_fma_f32 v[220:221], v[162:163], v[68:69], v[146:147] op_sel_hi:[1,1,0]
	v_subrev_u32_e32 v67, 26, v66
	v_subrev_u32_e32 v68, 25, v66
	v_cvt_f32_i32_e32 v67, v67
	v_cvt_f32_i32_e32 v68, v68
	v_subrev_u32_e32 v66, 27, v66
	v_cvt_f32_i32_e32 v69, v66
	v_and_b32_e32 v67, 0x7fffffff, v67
	v_and_b32_e32 v66, 0x7fffffff, v68
	v_mov_b32_e32 v81, v210
	v_pk_fma_f32 v[222:223], v[162:163], v[66:67], v[146:147] op_sel_hi:[1,1,0]
	v_fma_f32 v224, -v158, |v69|, v146
	v_mov_b64_e32 v[66:67], v[80:81]
	v_mov_b64_e32 v[68:69], v[82:83]
	v_mov_b64_e32 v[70:71], v[84:85]
	v_mov_b64_e32 v[72:73], v[86:87]
	v_mov_b64_e32 v[74:75], v[88:89]
	v_mov_b64_e32 v[76:77], v[90:91]
	v_mov_b64_e32 v[78:79], v[92:93]
	v_mov_b64_e32 v[80:81], v[94:95]
	v_mov_b32_e32 v68, v211
	v_mov_b32_e32 v69, v212
	v_mov_b32_e32 v70, v213
	v_mov_b32_e32 v71, v214
	v_mov_b32_e32 v72, v215
	v_mov_b32_e32 v73, v216
	v_mov_b32_e32 v74, v217
	v_mov_b32_e32 v75, v218
	v_mov_b32_e32 v76, v219
	v_mov_b32_e32 v77, v220
	v_mov_b32_e32 v78, v221
	v_mov_b32_e32 v79, v222
	v_mov_b32_e32 v80, v223
	v_mov_b32_e32 v81, v224
	s_branch .LBB0_220
.LBB0_219:
	v_cndmask_b32_e64 v244, -v158, v158, s[48:49]
	v_fma_f32 v66, 0, v244, v80
	v_add_f32_e32 v67, v244, v80
	v_pk_fma_f32 v[68:69], v[244:245], s[26:27], v[80:81] op_sel_hi:[0,1,0]
	v_pk_fma_f32 v[70:71], v[244:245], s[28:29], v[80:81] op_sel_hi:[0,1,0]
	v_pk_fma_f32 v[72:73], v[244:245], s[30:31], v[80:81] op_sel_hi:[0,1,0]
	v_pk_fma_f32 v[74:75], v[244:245], s[34:35], v[80:81] op_sel_hi:[0,1,0]
	v_pk_fma_f32 v[76:77], v[244:245], s[36:37], v[80:81] op_sel_hi:[0,1,0]
	v_pk_fma_f32 v[78:79], v[244:245], s[14:15], v[80:81] op_sel_hi:[0,1,0]
	v_pk_fma_f32 v[80:81], v[244:245], s[10:11], v[80:81] op_sel_hi:[0,1,0]

.LBB0_234:
	v_mfma_f32_32x32x16_bf16 v[50:65], v[130:133], v[66:69], v[50:65]
	ds_read_b128 v[182:185], v169
	ds_read_b128 v[198:201], v170
	ds_read_b128 v[202:205], v171
	v_exp_f32_e32 v149, v82
	v_exp_f32_e32 v150, v83
	s_add_i32 s0, s97, 0xffffff80
	s_and_b32 s0, s0, 0xf80
	s_cmp_lt_u32 s0, s84
	s_cselect_b64 s[44:45], -1, 0
	s_cmp_lg_u32 s0, s84
	v_mfma_f32_32x32x16_bf16 v[34:49], v[126:129], v[66:69], v[34:49]
	ds_read_b128 v[206:209], v172
	ds_read_b64_tr_b16 v[130:131], v173 offset:57344
	ds_read_b64_tr_b16 v[132:133], v174 offset:57344
	v_exp_f32_e32 v151, v84
	v_exp_f32_e32 v152, v85
	v_mfma_f32_32x32x16_bf16 v[18:33], v[122:125], v[66:69], v[18:33]
	ds_read_b64_tr_b16 v[126:127], v175 offset:57344
	ds_read_b64_tr_b16 v[128:129], v176 offset:57344
	ds_read_b64_tr_b16 v[122:123], v177 offset:57344
	v_exp_f32_e32 v153, v86
	v_exp_f32_e32 v164, v87
	v_mfma_f32_32x32x16_bf16 v[2:17], v[118:121], v[66:69], v[2:17]
	ds_read_b64_tr_b16 v[124:125], v178 offset:57344
	ds_read_b64_tr_b16 v[118:119], v179 offset:57344
	ds_read_b64_tr_b16 v[120:121], v180 offset:57344
	v_exp_f32_e32 v181, v88
	v_exp_f32_e32 v225, v89
	v_or_b32_e32 v66, s0, v166
	v_sub_u32_e32 v66, v167, v66
	v_cvt_f32_i32_e32 v67, v66
	v_fma_f32 v80, -v158, |v67|, v146
	v_mfma_f32_32x32x16_bf16 v[50:65], v[114:117], v[70:73], v[50:65]
	ds_read_b64_tr_b16 v[114:115], v173 offset:61440
	ds_read_b64_tr_b16 v[116:117], v174 offset:61440
	v_exp_f32_e32 v226, v90
	v_exp_f32_e32 v227, v91
	v_mfma_f32_32x32x16_bf16 v[34:49], v[134:137], v[70:73], v[34:49]
	ds_read_b64_tr_b16 v[134:135], v175 offset:61440
	ds_read_b64_tr_b16 v[136:137], v176 offset:61440
	v_exp_f32_e32 v239, v92
	v_exp_f32_e32 v240, v93
	v_mfma_f32_32x32x16_bf16 v[18:33], v[138:141], v[70:73], v[18:33]
	ds_read_b64_tr_b16 v[138:139], v177 offset:61440
	ds_read_b64_tr_b16 v[140:141], v178 offset:61440
	v_exp_f32_e32 v241, v94
	v_exp_f32_e32 v242, v95
	v_mfma_f32_32x32x16_bf16 v[2:17], v[142:145], v[70:73], v[2:17]
	ds_read_b64_tr_b16 v[142:143], v179 offset:61440
	ds_read_b64_tr_b16 v[144:145], v180 offset:61440
	v_exp_f32_e32 v243, v96
	v_exp_f32_e32 v246, v97
	s_cbranch_scc1 .LBB0_236
	v_add_u32_e32 v67, -2, v66
	v_cvt_f32_i32_e32 v67, v67
	v_add_u32_e32 v68, -1, v66
	v_cvt_f32_i32_e32 v68, v68
	v_add_u32_e32 v70, -8, v66
	v_and_b32_e32 v69, 0x7fffffff, v67
	v_add_u32_e32 v67, -3, v66
	v_cvt_f32_i32_e32 v67, v67
	v_cvt_f32_i32_e32 v70, v70
	v_and_b32_e32 v68, 0x7fffffff, v68
	v_pk_fma_f32 v[210:211], v[162:163], v[68:69], v[146:147] op_sel_hi:[1,1,0]
	v_and_b32_e32 v68, 0x7fffffff, v67
	v_add_u32_e32 v67, -10, v66
	v_cvt_f32_i32_e32 v67, v67
	v_and_b32_e32 v69, 0x7fffffff, v70
	v_pk_fma_f32 v[212:213], v[162:163], v[68:69], v[146:147] op_sel_hi:[1,1,0]
	v_add_u32_e32 v68, -9, v66
	v_cvt_f32_i32_e32 v68, v68
	v_and_b32_e32 v69, 0x7fffffff, v67
	v_add_u32_e32 v67, -16, v66
	v_cvt_f32_i32_e32 v67, v67
	v_add_u32_e32 v70, -11, v66
	v_cvt_f32_i32_e32 v70, v70
	v_and_b32_e32 v68, 0x7fffffff, v68
	v_pk_fma_f32 v[214:215], v[162:163], v[68:69], v[146:147] op_sel_hi:[1,1,0]
	v_and_b32_e32 v69, 0x7fffffff, v67
	v_subrev_u32_e32 v67, 18, v66
	v_cvt_f32_i32_e32 v67, v67
	v_and_b32_e32 v68, 0x7fffffff, v70
	v_pk_fma_f32 v[216:217], v[162:163], v[68:69], v[146:147] op_sel_hi:[1,1,0]
	v_subrev_u32_e32 v68, 17, v66
	v_cvt_f32_i32_e32 v68, v68
	v_and_b32_e32 v69, 0x7fffffff, v67
	v_subrev_u32_e32 v67, 24, v66
	v_subrev_u32_e32 v70, 19, v66
	v_cvt_f32_i32_e32 v67, v67
	v_cvt_f32_i32_e32 v70, v70
	v_and_b32_e32 v68, 0x7fffffff, v68
	v_pk_fma_f32 v[218:219], v[162:163], v[68:69], v[146:147] op_sel_hi:[1,1,0]
	v_and_b32_e32 v69, 0x7fffffff, v67
	v_and_b32_e32 v68, 0x7fffffff, v70
	v_pk_fma_f32 v[220:221], v[162:163], v[68:69], v[146:147] op_sel_hi:[1,1,0]
	v_subrev_u32_e32 v67, 26, v66
	v_subrev_u32_e32 v68, 25, v66
	v_cvt_f32_i32_e32 v67, v67
	v_cvt_f32_i32_e32 v68, v68
	v_subrev_u32_e32 v66, 27, v66
	v_cvt_f32_i32_e32 v69, v66
	v_and_b32_e32 v67, 0x7fffffff, v67
	v_and_b32_e32 v66, 0x7fffffff, v68
	v_mov_b32_e32 v81, v210
	v_pk_fma_f32 v[222:223], v[162:163], v[66:67], v[146:147] op_sel_hi:[1,1,0]
	v_fma_f32 v224, -v158, |v69|, v146
	v_mov_b64_e32 v[66:67], v[80:81]
	v_mov_b64_e32 v[68:69], v[82:83]
	v_mov_b64_e32 v[70:71], v[84:85]
	v_mov_b64_e32 v[72:73], v[86:87]
	v_mov_b64_e32 v[74:75], v[88:89]
	v_mov_b64_e32 v[76:77], v[90:91]
	v_mov_b64_e32 v[78:79], v[92:93]
	v_mov_b64_e32 v[80:81], v[94:95]
	v_mov_b32_e32 v68, v211
	v_mov_b32_e32 v69, v212
	v_mov_b32_e32 v70, v213
	v_mov_b32_e32 v71, v214
	v_mov_b32_e32 v72, v215
	v_mov_b32_e32 v73, v216
	v_mov_b32_e32 v74, v217
	v_mov_b32_e32 v75, v218
	v_mov_b32_e32 v76, v219
	v_mov_b32_e32 v77, v220
	v_mov_b32_e32 v78, v221
	v_mov_b32_e32 v79, v222
	v_mov_b32_e32 v80, v223
	v_mov_b32_e32 v81, v224
	s_branch .LBB0_237
